# HGRN B state update: decay-vector LDS reads issued first so the accumulator scaling overlaps the fragment reads (on top of v36)
# speedup vs baseline: 1.0083x; 1.0083x over previous
; #define MFMA16(a, b, c) __builtin_amdgcn_mfma_f32_16x16x32_bf16((a), (b), (c), 0, 0, 0)
; __device__ __forceinline__ bf16x8 pack8(f32x4 a, f32x4 b) { u32x4 w = {pk2(a[0], a[1]), pk2(a[2], a[3]), pk2(b[0], b[1]), pk2(b[2], b[3])}; return __builtin_bit_cast(bf16x8, w); }
; __device__ __forceinline__ bf16x8 cat8(bf16x4 lo, bf16x4 hi) { return __builtin_shufflevector(lo, hi, 0, 1, 2, 3, 4, 5, 6, 7); }
; __device__ __forceinline__ void hgrn_b(unsigned char* lds, const Params& p, int jl, const bf16_t* proj, bf16_t* mix, const float* dbuf, const bf16_t* scr, const float* useg, const float* dseg, int blk, int G, int tid) {
;     ...
;             const bf16_t* qh = QH + buf * (64 * 136); const bf16_t* kt = KT + buf * (128 * 72); const bf16_t* vt = VT + buf * (128 * 72); const float* dl = DL + buf * 128;
;             f32x4 oT[4];
;             { bf16x8 sa[4];
; #pragma unroll
;               for (int k2 = 0; k2 < 4; ++k2) sa[k2] = pack8(S[2 * k2], S[2 * k2 + 1]);
; #pragma unroll
;               for (int th = 0; th < 2; ++th) { bf16x8 qfr[2][4];
; #pragma unroll
;                   for (int t2 = 0; t2 < 2; ++t2)
; #pragma unroll
;                       for (int k2 = 0; k2 < 4; ++k2) { const bf16_t* qp = qh + ((th * 2 + t2) * 16 + fr) * 136 + k2 * 32 + fq * 4; qfr[t2][k2] = cat8(*(const bf16x4*)qp, *(const bf16x4*)(qp + 16)); }
;                   __builtin_amdgcn_sched_barrier(0);
; #pragma unroll
;                   for (int t2 = 0; t2 < 2; ++t2) oT[th * 2 + t2] = (f32x4){0.f, 0.f, 0.f, 0.f};
; #pragma unroll
;                   for (int k2 = 0; k2 < 4; ++k2)
; #pragma unroll
;                       for (int t2 = 0; t2 < 2; ++t2) oT[th * 2 + t2] = MFMA16(sa[k2], qfr[t2][k2], oT[th * 2 + t2]);
;                   __builtin_amdgcn_sched_barrier(0); } }
;             { bf16x8 vb[2];
; #pragma unroll
;               for (int ks = 0; ks < 2; ++ks) vb[ks] = *(const bf16x8*)(vt + (w * 16 + fr) * 72 + ks * 32 + fq * 8);
; #pragma unroll
;               for (int kh2 = 0; kh2 < 2; ++kh2) { bf16x8 kf[4][2]; f32x4 dv[4];
; #pragma unroll
;                   for (int k3 = 0; k3 < 4; ++k3) { dv[k3] = *(const f32x4*)(dl + (kh2 * 4 + k3) * 16 + fq * 4);
; #pragma unroll
;                       for (int ks = 0; ks < 2; ++ks) kf[k3][ks] = *(const bf16x8*)(kt + ((kh2 * 4 + k3) * 16 + fr) * 72 + ks * 32 + fq * 8); }
.LBB0_412:
	s_or_b64 exec, exec, s[16:17]
	s_and_b32 s19, s19, 1
	s_mul_i32 s16, s19, 0x4400
	v_add3_u32 v0, v125, s16, v180
	v_add_u32_e32 v152, 0x1000, v0
	ds_read_b64 v[68:69], v0
	ds_read_b64 v[70:71], v0 offset:32
	ds_read_b64 v[184:185], v0 offset:64
	ds_read_b64 v[186:187], v0 offset:96
	ds_read_b64 v[188:189], v0 offset:128
	ds_read_b64 v[190:191], v0 offset:160
	ds_read_b64 v[192:193], v0 offset:192
	ds_read_b64 v[194:195], v0 offset:224
	ds_read_b64 v[196:197], v152 offset:256
	ds_read_b64 v[198:199], v152 offset:288
	ds_read_b64 v[200:201], v152 offset:320
	ds_read_b64 v[202:203], v152 offset:352
	ds_read_b64 v[204:205], v152 offset:384
	ds_read_b64 v[206:207], v152 offset:416
	v_cvt_pk_bf16_f32 v72, v36, v37
	v_cvt_pk_bf16_f32 v73, v38, v39
	v_cvt_pk_bf16_f32 v74, v40, v41
	v_cvt_pk_bf16_f32 v75, v42, v43
	v_cvt_pk_bf16_f32 v76, v44, v45
	v_cvt_pk_bf16_f32 v77, v46, v47
	v_cvt_pk_bf16_f32 v78, v48, v49
	v_cvt_pk_bf16_f32 v79, v50, v51
	v_cvt_pk_bf16_f32 v166, v56, v57
	v_cvt_pk_bf16_f32 v167, v58, v59
	v_cvt_pk_bf16_f32 v164, v52, v53
	v_cvt_pk_bf16_f32 v165, v54, v55
	v_cvt_pk_bf16_f32 v220, v60, v61
	v_cvt_pk_bf16_f32 v221, v62, v63
	v_cvt_pk_bf16_f32 v222, v64, v65
	v_cvt_pk_bf16_f32 v223, v66, v67
	s_waitcnt lgkmcnt(12)
	ds_read_b64 v[216:217], v152 offset:448
	ds_read_b64 v[218:219], v152 offset:480
	v_mfma_f32_16x16x32_bf16 v[68:71], v[72:75], v[68:71], 0
	s_waitcnt lgkmcnt(6)
	v_mfma_f32_16x16x32_bf16 v[196:199], v[72:75], v[196:199], 0
	v_mfma_f32_16x16x32_bf16 v[68:71], v[76:79], v[184:187], v[68:71]
	s_waitcnt lgkmcnt(4)
	v_mfma_f32_16x16x32_bf16 v[184:187], v[76:79], v[200:203], v[196:199]
	v_mfma_f32_16x16x32_bf16 v[68:71], v[164:167], v[188:191], v[68:71]
	s_waitcnt lgkmcnt(2)
	v_mfma_f32_16x16x32_bf16 v[184:187], v[164:167], v[204:207], v[184:187]
	v_mfma_f32_16x16x32_bf16 v[188:191], v[220:223], v[192:195], v[68:71]
	s_waitcnt lgkmcnt(0)
	v_mfma_f32_16x16x32_bf16 v[68:71], v[220:223], v[216:219], v[184:187]
	v_add_u32_e32 v152, 0x2000, v0
	v_add_u32_e32 v0, 0x3000, v0
	s_nop 2
	ds_read_b64 v[184:185], v152 offset:512
	ds_read_b64 v[186:187], v152 offset:544
	ds_read_b64 v[192:193], v152 offset:576
	ds_read_b64 v[194:195], v152 offset:608
	ds_read_b64 v[196:197], v152 offset:640
	ds_read_b64 v[198:199], v152 offset:672
	ds_read_b64 v[200:201], v152 offset:704
	ds_read_b64 v[202:203], v152 offset:736
	ds_read_b64 v[204:205], v0 offset:768
	ds_read_b64 v[206:207], v0 offset:800
	ds_read_b64 v[216:217], v0 offset:832
	ds_read_b64 v[218:219], v0 offset:864
	ds_read_b64 v[224:225], v0 offset:896
	ds_read_b64 v[226:227], v0 offset:928
	s_waitcnt lgkmcnt(12)
	ds_read_b64 v[228:229], v0 offset:960
	ds_read_b64 v[230:231], v0 offset:992
	v_mfma_f32_16x16x32_bf16 v[184:187], v[72:75], v[184:187], 0
	s_waitcnt lgkmcnt(6)
	v_mfma_f32_16x16x32_bf16 v[72:75], v[72:75], v[204:207], 0
	v_mfma_f32_16x16x32_bf16 v[184:187], v[76:79], v[192:195], v[184:187]
	s_waitcnt lgkmcnt(4)
	v_mfma_f32_16x16x32_bf16 v[72:75], v[76:79], v[216:219], v[72:75]
	v_mfma_f32_16x16x32_bf16 v[76:79], v[164:167], v[196:199], v[184:187]
	s_waitcnt lgkmcnt(2)
	v_mfma_f32_16x16x32_bf16 v[72:75], v[164:167], v[224:227], v[72:75]
	v_mfma_f32_16x16x32_bf16 v[76:79], v[220:223], v[200:203], v[76:79]
	s_waitcnt lgkmcnt(0)
	v_mfma_f32_16x16x32_bf16 v[72:75], v[220:223], v[228:231], v[72:75]
	s_mul_i32 s16, s19, 0x4800
	v_lshl_add_u32 v248, s19, 9, v171
	ds_read_b128 v[200:203], v248
	ds_read_b128 v[204:207], v248 offset:64
	ds_read_b128 v[232:235], v248 offset:128
	ds_read_b128 v[236:239], v248 offset:192
	v_add_u32_e32 v0, s16, v170
	v_add3_u32 v152, v172, s16, v181
	ds_read_b128 v[164:167], v0
	ds_read_b128 v[184:187], v0 offset:64
	v_lshl_add_u32 v0, s19, 9, v171
	ds_read_b128 v[192:195], v152 offset:34816
	ds_read_b128 v[196:199], v152 offset:34880
	ds_read_b128 v[216:219], v152 offset:37120
	ds_read_b128 v[220:223], v152 offset:37184
	ds_read_b128 v[224:227], v152 offset:39424
	ds_read_b128 v[228:231], v152 offset:39488
	ds_read_b128 v[240:243], v152 offset:41728
	ds_read_b128 v[244:247], v152 offset:41792
	s_waitcnt lgkmcnt(13)
; #define MFMA16(a, b, c) __builtin_amdgcn_mfma_f32_16x16x32_bf16((a), (b), (c), 0, 0, 0)
; __device__ __forceinline__ void hgrn_b(unsigned char* lds, const Params& p, int jl, const bf16_t* proj, bf16_t* mix, const float* dbuf, const bf16_t* scr, const float* useg, const float* dseg, int blk, int G, int tid) {
;     ...
;                   __builtin_amdgcn_sched_barrier(0);
; #pragma unroll
;                   for (int k3 = 0; k3 < 4; ++k3) S[kh2 * 4 + k3] = S[kh2 * 4 + k3] * dv[k3];
; #pragma unroll
;                   for (int ks = 0; ks < 2; ++ks)
; #pragma unroll
;                       for (int k3 = 0; k3 < 4; ++k3) S[kh2 * 4 + k3] = MFMA16(kf[k3][ks], vb[ks], S[kh2 * 4 + k3]);
;                   __builtin_amdgcn_sched_barrier(0); } }
; #pragma unroll
;             for (int tt = 0; tt < 4; ++tt) { float ss = 0.f;
; #pragma unroll
;                 for (int j = 0; j < 4; ++j) { const unsigned wv = oin[tt][j >> 1]; const float oi = __uint_as_float((j & 1) ? (wv & 0xffff0000u) : (wv << 16)); const float ov = oT[tt][j] + oi; oT[tt][j] = ov; ss += ov * ov; }
;                 ss += __shfl_xor(ss, 16); ss += __shfl_xor(ss, 32);
;                 if (fq == 0) PART[(tt * 16 + fr) * 8 + w] = ss; }
	v_mul_f32_e32 v36, v36, v200
	v_mul_f32_e32 v37, v37, v201
	v_mul_f32_e32 v38, v38, v202
	v_mul_f32_e32 v39, v39, v203
	s_waitcnt lgkmcnt(12)
	v_mul_f32_e32 v40, v40, v204
	v_mul_f32_e32 v41, v41, v205
	v_mul_f32_e32 v42, v42, v206
	v_mul_f32_e32 v43, v43, v207
	s_waitcnt lgkmcnt(11)
	v_mul_f32_e32 v44, v44, v232
	v_mul_f32_e32 v45, v45, v233
	v_mul_f32_e32 v46, v46, v234
	v_mul_f32_e32 v47, v47, v235
	s_waitcnt lgkmcnt(10)
	v_mul_f32_e32 v48, v48, v236
	v_mul_f32_e32 v49, v49, v237
	v_mul_f32_e32 v50, v50, v238
	v_mul_f32_e32 v51, v51, v239
	s_waitcnt lgkmcnt(2)
	v_mfma_f32_16x16x32_bf16 v[36:39], v[192:195], v[164:167], v[36:39]
	v_mfma_f32_16x16x32_bf16 v[40:43], v[216:219], v[164:167], v[40:43]
	v_mfma_f32_16x16x32_bf16 v[44:47], v[224:227], v[164:167], v[44:47]
	s_waitcnt lgkmcnt(1)
	v_mfma_f32_16x16x32_bf16 v[48:51], v[240:243], v[164:167], v[48:51]
	v_mfma_f32_16x16x32_bf16 v[36:39], v[196:199], v[184:187], v[36:39]
	v_mfma_f32_16x16x32_bf16 v[40:43], v[220:223], v[184:187], v[40:43]
	v_mfma_f32_16x16x32_bf16 v[44:47], v[228:231], v[184:187], v[44:47]
	s_waitcnt lgkmcnt(0)
	v_mfma_f32_16x16x32_bf16 v[48:51], v[244:247], v[184:187], v[48:51]
	ds_read_b128 v[200:203], v0 offset:256
	ds_read_b128 v[204:207], v0 offset:320
	ds_read_b128 v[232:235], v0 offset:384
	ds_read_b128 v[236:239], v0 offset:448
	ds_read_b128 v[192:195], v152 offset:44032
	ds_read_b128 v[196:199], v152 offset:44096
	ds_read_b128 v[216:219], v152 offset:46336
	ds_read_b128 v[220:223], v152 offset:46400
	ds_read_b128 v[224:227], v152 offset:48640
	ds_read_b128 v[228:231], v152 offset:48704
	ds_read_b128 v[240:243], v152 offset:50944
	ds_read_b128 v[244:247], v152 offset:51008
	s_waitcnt lgkmcnt(11)
	v_mul_f32_e32 v52, v52, v200
	v_mul_f32_e32 v53, v53, v201
	v_mul_f32_e32 v54, v54, v202
	v_mul_f32_e32 v55, v55, v203
	s_waitcnt lgkmcnt(10)
	v_mul_f32_e32 v56, v56, v204
	v_mul_f32_e32 v57, v57, v205
	v_mul_f32_e32 v58, v58, v206
	v_mul_f32_e32 v59, v59, v207
	s_waitcnt lgkmcnt(9)
	v_mul_f32_e32 v60, v60, v232
	v_mul_f32_e32 v61, v61, v233
	v_mul_f32_e32 v62, v62, v234
	v_mul_f32_e32 v63, v63, v235
	s_waitcnt lgkmcnt(8)
	v_mul_f32_e32 v64, v64, v236
	v_mul_f32_e32 v65, v65, v237
	v_mul_f32_e32 v66, v66, v238
	v_mul_f32_e32 v67, v67, v239
	s_waitcnt lgkmcnt(2)
	v_mfma_f32_16x16x32_bf16 v[52:55], v[192:195], v[164:167], v[52:55]
	v_mfma_f32_16x16x32_bf16 v[56:59], v[216:219], v[164:167], v[56:59]
	v_mfma_f32_16x16x32_bf16 v[60:63], v[224:227], v[164:167], v[60:63]
	s_waitcnt lgkmcnt(1)
	v_mfma_f32_16x16x32_bf16 v[64:67], v[240:243], v[164:167], v[64:67]
	v_mfma_f32_16x16x32_bf16 v[52:55], v[196:199], v[184:187], v[52:55]
	v_mfma_f32_16x16x32_bf16 v[56:59], v[220:223], v[184:187], v[56:59]
	v_mfma_f32_16x16x32_bf16 v[60:63], v[228:231], v[184:187], v[60:63]
	s_waitcnt lgkmcnt(0)
	v_mfma_f32_16x16x32_bf16 v[64:67], v[244:247], v[184:187], v[64:67]
	s_waitcnt vmcnt(3)
	v_lshlrev_b32_e32 v152, 16, v162
	v_and_b32_e32 v153, 0xffff0000, v162
	v_pk_add_f32 v[166:167], v[188:189], v[152:153]
	v_lshlrev_b32_e32 v162, 16, v163
	v_and_b32_e32 v163, 0xffff0000, v163
	v_pk_mul_f32 v[152:153], v[166:167], v[166:167]
	v_pk_add_f32 v[168:169], v[190:191], v[162:163]
	v_add_f32_e32 v0, v152, v153
	v_pk_mul_f32 v[162:163], v[168:169], v[168:169]
	s_nop 0
	v_add_f32_e32 v0, v162, v0
	v_add_f32_e32 v0, v163, v0
	v_mov_b32_e32 v152, v0
	s_nop 1
	v_permlane16_swap_b32_e32 v152, v0
	v_add_f32_e32 v0, v0, v152
	v_mov_b32_e32 v162, v0
	s_nop 1
	v_permlane32_swap_b32_e32 v162, v0
	v_add_f32_e32 v0, v0, v162
	s_and_saveexec_b64 s[16:17], s[4:5]
	s_cbranch_execz .LBB0_414
	ds_write_b32 v176, v0
